# od_win epilogue: 124 packed f32 VALU ops split into scalar pairs (packed fp32 beside MFMAs costs more than two singles)
# baseline (speedup 1.0000x reference)
.LBB0_263:
	s_cmp_lt_u32 s8, 8
	s_cselect_b64 vcc, -1, 0
	s_and_b64 s[6:7], vcc, exec
	s_mov_b32 s6, 0x373c000
	v_readlane_b32 s12, v253, 12
	s_cselect_b32 s6, s6, 0x5b3c000
	v_readlane_b32 s18, v253, 18
	v_readlane_b32 s19, v253, 19
	v_readlane_b32 s20, v253, 20
	v_readlane_b32 s21, v253, 21
	s_cselect_b32 s8, s18, s20
	s_cselect_b32 s11, s19, s21
	s_add_u32 s6, s48, s6
	s_addc_u32 s7, s49, 0
	v_lshlrev_b32_e32 v66, 3, v111
	s_add_u32 s10, s8, s0
	v_and_b32_e32 v83, 56, v66
	s_addc_u32 s11, s11, s1
	v_lshlrev_b32_e32 v66, 2, v83
	global_load_dwordx4 v[70:73], v66, s[10:11]
	s_nop 0
	global_load_dwordx4 v[66:69], v66, s[10:11] offset:16
	v_and_b32_e32 v75, 64, v200
	v_xor_b32_e32 v74, 1, v200
	v_add_u32_e32 v95, 64, v75
	v_cndmask_b32_e32 v80, 1.0, v197, vcc
	v_cmp_lt_i32_e32 vcc, v74, v95
	v_mul_f32_e32 v76, v58, v58
	v_mul_f32_e32 v77, v59, v59
	v_mul_f32_e32 v88, v50, v50
	v_mul_f32_e32 v89, v51, v51
	v_cndmask_b32_e32 v74, v200, v74, vcc
	v_lshlrev_b32_e32 v82, 2, v74
	v_xor_b32_e32 v74, 2, v200
	v_cmp_lt_i32_e32 vcc, v74, v95
	v_mul_f32_e32 v86, v52, v52
	v_mul_f32_e32 v87, v53, v53
	v_mov_b32_e32 v90, v88
	v_cndmask_b32_e32 v74, v200, v74, vcc
	v_lshlrev_b32_e32 v81, 2, v74
	v_mul_f32_e32 v74, v60, v60
	v_mul_f32_e32 v75, v61, v61
	v_mov_b32_e32 v91, v76
	v_mov_b32_e32 v76, v89
	v_add_f32_e32 v76, v90, v76
	v_add_f32_e32 v77, v91, v77
	v_mov_b32_e32 v92, v86
	v_mov_b32_e32 v93, v74
	v_mul_f32_e32 v84, v62, v62
	v_mul_f32_e32 v85, v63, v63
	v_mul_f32_e32 v90, v54, v54
	v_mul_f32_e32 v91, v55, v55
	v_add_f32_e32 v76, v92, v76
	v_add_f32_e32 v77, v93, v77
	v_mov_b32_e32 v74, v87
	v_add_f32_e32 v74, v74, v76
	v_add_f32_e32 v75, v75, v77
	v_mov_b32_e32 v76, v90
	v_mov_b32_e32 v77, v84
	v_mul_f32_e32 v78, v64, v64
	v_mul_f32_e32 v79, v65, v65
	v_mul_f32_e32 v88, v56, v56
	v_mul_f32_e32 v89, v57, v57
	v_add_f32_e32 v74, v76, v74
	v_add_f32_e32 v75, v77, v75
	v_mov_b32_e32 v84, v91
	v_add_f32_e32 v74, v84, v74
	v_add_f32_e32 v75, v85, v75
	v_mov_b32_e32 v76, v88
	v_mov_b32_e32 v77, v78
	v_add_f32_e32 v74, v76, v74
	v_add_f32_e32 v75, v77, v75
	v_mov_b32_e32 v78, v89
	v_add_f32_e32 v74, v78, v74
	v_add_f32_e32 v75, v79, v75
	v_xor_b32_e32 v96, 4, v200
	v_cmp_lt_i32_e32 vcc, v96, v95
	v_bfe_u32 v94, v111, 3, 1
	v_ashrrev_i32_e32 v117, 31, v116
	v_cndmask_b32_e32 v78, v200, v96, vcc
	v_lshlrev_b32_e32 v92, 2, v78
	v_lshl_or_b32 v78, s3, 4, v94
	s_waitcnt lgkmcnt(0)
	v_add_f32_dpp v76, v74, v74 quad_perm:[1,0,3,2] row_mask:0xf bank_mask:0xf
	v_add_f32_dpp v77, v75, v75 quad_perm:[1,0,3,2] row_mask:0xf bank_mask:0xf
	v_or_b32_e32 v84, s9, v78
	v_readlane_b32 s8, v255, 40
	v_readlane_b32 s9, v255, 41
	v_mov_b32_e32 v75, v1
	v_mov_b32_e32 v74, s8
	s_movk_i32 s3, 0x900
	s_waitcnt lgkmcnt(0)
	v_add_f32_dpp v78, v76, v76 quad_perm:[2,3,0,1] row_mask:0xf bank_mask:0xf
	v_add_f32_dpp v79, v77, v77 quad_perm:[2,3,0,1] row_mask:0xf bank_mask:0xf
	v_mad_i64_i32 v[74:75], s[8:9], v84, s3, v[74:75]
	v_lshlrev_b32_e32 v76, 1, v83
	v_mov_b32_e32 v77, v1
	v_lshl_add_u64 v[76:77], s[6:7], 0, v[76:77]
	s_mov_b32 s6, 0x358637bd
	s_waitcnt lgkmcnt(0)
	v_add_f32_dpp v84, v78, v78 row_half_mirror row_mask:0xf bank_mask:0xf
	v_add_f32_dpp v85, v79, v79 row_half_mirror row_mask:0xf bank_mask:0xf
	v_mov_b64_e32 v[78:79], s[6:7]
	s_mov_b32 s6, 0x3c800000
	v_pk_fma_f32 v[84:85], v[84:85], s[6:7], v[78:79] op_sel_hi:[1,0,0]
	v_lshl_add_u64 v[86:87], v[74:75], 0, v[116:117]
	v_mul_f32_e32 v83, 0x4b800000, v85
	v_cmp_gt_f32_e32 vcc, s33, v85
	v_lshlrev_b64 v[86:87], 7, v[86:87]
	v_lshl_add_u64 v[86:87], v[76:77], 0, v[86:87]
	v_cndmask_b32_e32 v83, v85, v83, vcc
	v_rsq_f32_e32 v83, v83
	v_readlane_b32 s13, v253, 13
	v_readlane_b32 s14, v253, 14
	v_readlane_b32 s15, v253, 15
	v_mul_f32_e32 v85, 0x45800000, v83
	v_cndmask_b32_e32 v83, v83, v85, vcc
	v_mul_f32_e32 v88, v80, v83
	s_waitcnt vmcnt(0)
	v_mul_f32_e32 v90, v70, v88
	v_mul_f32_e32 v91, v71, v88
	v_cmp_gt_f32_e32 vcc, s33, v84
	v_mul_f32_e32 v58, v58, v90
	v_mul_f32_e32 v59, v59, v91
	v_mul_f32_e32 v90, v72, v88
	v_mul_f32_e32 v91, v73, v88
	v_cvt_pk_bf16_f32 v58, v58, v59
	v_mul_f32_e32 v60, v60, v90
	v_mul_f32_e32 v61, v61, v91
	v_mul_f32_e32 v90, v66, v88
	v_mul_f32_e32 v91, v67, v88
	v_cvt_pk_bf16_f32 v59, v60, v61
	v_mul_f32_e32 v60, 0x4b800000, v84
	v_cndmask_b32_e32 v60, v84, v60, vcc
	v_rsq_f32_e32 v83, v60
	v_mul_f32_e32 v89, v69, v88
	v_mul_f32_e32 v88, v68, v88
	v_mul_f32_e32 v62, v62, v90
	v_mul_f32_e32 v63, v63, v91
	v_mul_f32_e32 v64, v64, v88
	v_mul_f32_e32 v65, v65, v89
	v_cvt_pk_bf16_f32 v60, v62, v63
	v_cvt_pk_bf16_f32 v61, v64, v65
	global_store_dwordx4 v[86:87], v[58:61], off
	v_mul_f32_e32 v86, v34, v34
	v_mul_f32_e32 v87, v35, v35
	v_mul_f32_e32 v84, v36, v36
	v_mul_f32_e32 v85, v37, v37
	v_mul_f32_e32 v58, 0x45800000, v83
	v_cndmask_b32_e32 v58, v83, v58, vcc
	v_mul_f32_e32 v58, v80, v58
	v_mul_f32_e32 v60, v70, v58
	v_mul_f32_e32 v61, v71, v58
	v_mov_b32_e32 v88, v86
	v_mul_f32_e32 v50, v50, v60
	v_mul_f32_e32 v51, v51, v61
	v_mul_f32_e32 v60, v72, v58
	v_mul_f32_e32 v61, v73, v58
	v_mov_b32_e32 v90, v84
	v_mul_f32_e32 v52, v52, v60
	v_mul_f32_e32 v53, v53, v61
	v_mul_f32_e32 v60, v66, v58
	v_mul_f32_e32 v61, v67, v58
	v_mul_f32_e32 v59, v69, v58
	v_mul_f32_e32 v58, v68, v58
	v_mul_f32_e32 v54, v54, v60
	v_mul_f32_e32 v55, v55, v61
	v_mul_f32_e32 v60, v42, v42
	v_mul_f32_e32 v61, v43, v43
	v_mul_f32_e32 v56, v56, v58
	v_mul_f32_e32 v57, v57, v59
	v_mul_f32_e32 v58, v44, v44
	v_mul_f32_e32 v59, v45, v45
	v_mov_b32_e32 v89, v60
	v_mov_b32_e32 v60, v87
	v_add_f32_e32 v60, v88, v60
	v_add_f32_e32 v61, v89, v61
	v_mov_b32_e32 v91, v58
	v_mul_f32_e32 v64, v46, v46
	v_mul_f32_e32 v65, v47, v47
	v_mul_f32_e32 v88, v38, v38
	v_mul_f32_e32 v89, v39, v39
	v_add_f32_e32 v60, v90, v60
	v_add_f32_e32 v61, v91, v61
	v_mov_b32_e32 v58, v85
	v_add_f32_e32 v58, v58, v60
	v_add_f32_e32 v59, v59, v61
	v_mov_b32_e32 v60, v88
	v_mov_b32_e32 v61, v64
	v_mul_f32_e32 v62, v48, v48
	v_mul_f32_e32 v63, v49, v49
	v_mul_f32_e32 v86, v40, v40
	v_mul_f32_e32 v87, v41, v41
	v_add_f32_e32 v58, v60, v58
	v_add_f32_e32 v59, v61, v59
	v_mov_b32_e32 v64, v89
	v_add_f32_e32 v58, v64, v58
	v_add_f32_e32 v59, v65, v59
	v_mov_b32_e32 v60, v86
	v_mov_b32_e32 v61, v62
	v_add_f32_e32 v58, v60, v58
	v_add_f32_e32 v59, v61, v59
	v_mov_b32_e32 v62, v87
	v_add_f32_e32 v58, v62, v58
	v_add_f32_e32 v59, v63, v59
	v_cvt_pk_bf16_f32 v50, v50, v51
	v_cvt_pk_bf16_f32 v51, v52, v53
	v_cvt_pk_bf16_f32 v52, v54, v55
	v_add_u32_e32 v62, 16, v116
	s_waitcnt lgkmcnt(0)
	v_add_f32_dpp v54, v58, v58 quad_perm:[1,0,3,2] row_mask:0xf bank_mask:0xf
	v_add_f32_dpp v55, v59, v59 quad_perm:[1,0,3,2] row_mask:0xf bank_mask:0xf
	v_ashrrev_i32_e32 v63, 31, v62
	v_cvt_pk_bf16_f32 v53, v56, v57
	v_lshl_add_u64 v[56:57], v[74:75], 0, v[62:63]
	v_lshlrev_b64 v[56:57], 7, v[56:57]
	s_waitcnt lgkmcnt(0)
	v_add_f32_dpp v54, v54, v54 quad_perm:[2,3,0,1] row_mask:0xf bank_mask:0xf
	v_add_f32_dpp v55, v55, v55 quad_perm:[2,3,0,1] row_mask:0xf bank_mask:0xf
	v_lshl_add_u64 v[56:57], v[76:77], 0, v[56:57]
	global_store_dwordx4 v[56:57], v[50:53], off
	v_readlane_b32 s16, v253, 16
	v_readlane_b32 s17, v253, 17
	s_waitcnt lgkmcnt(0)
	v_add_f32_dpp v52, v54, v54 row_half_mirror row_mask:0xf bank_mask:0xf
	v_add_f32_dpp v53, v55, v55 row_half_mirror row_mask:0xf bank_mask:0xf
	v_add_u32_e32 v50, 32, v116
	v_pk_fma_f32 v[52:53], v[52:53], s[6:7], v[78:79] op_sel_hi:[1,0,0]
	v_ashrrev_i32_e32 v51, 31, v50
	v_mul_f32_e32 v54, 0x4b800000, v53
	v_cmp_gt_f32_e32 vcc, s33, v53
	v_lshl_add_u64 v[50:51], v[74:75], 0, v[50:51]
	v_lshlrev_b64 v[50:51], 7, v[50:51]
	v_cndmask_b32_e32 v53, v53, v54, vcc
	v_rsq_f32_e32 v53, v53
	v_lshl_add_u64 v[50:51], v[76:77], 0, v[50:51]
	v_readlane_b32 s22, v253, 22
	v_readlane_b32 s23, v253, 23
	v_mul_f32_e32 v54, 0x45800000, v53
	v_cndmask_b32_e32 v53, v53, v54, vcc
	v_mul_f32_e32 v54, v80, v53
	v_mul_f32_e32 v56, v70, v54
	v_mul_f32_e32 v57, v71, v54
	v_cmp_gt_f32_e32 vcc, s33, v52
	v_mul_f32_e32 v42, v42, v56
	v_mul_f32_e32 v43, v43, v57
	v_mul_f32_e32 v56, v72, v54
	v_mul_f32_e32 v57, v73, v54
	v_cvt_pk_bf16_f32 v42, v42, v43
	v_mul_f32_e32 v44, v44, v56
	v_mul_f32_e32 v45, v45, v57
	v_mul_f32_e32 v56, v66, v54
	v_mul_f32_e32 v57, v67, v54
	v_cvt_pk_bf16_f32 v43, v44, v45
	v_mul_f32_e32 v44, 0x4b800000, v52
	v_cndmask_b32_e32 v44, v52, v44, vcc
	v_rsq_f32_e32 v52, v44
	v_mul_f32_e32 v55, v69, v54
	v_mul_f32_e32 v54, v68, v54
	v_mul_f32_e32 v46, v46, v56
	v_mul_f32_e32 v47, v47, v57
	v_mul_f32_e32 v48, v48, v54
	v_mul_f32_e32 v49, v49, v55
	v_cvt_pk_bf16_f32 v44, v46, v47
	v_cvt_pk_bf16_f32 v45, v48, v49
	global_store_dwordx4 v[50:51], v[42:45], off
	v_mul_f32_e32 v50, v20, v20
	v_mul_f32_e32 v51, v21, v21
	v_mul_f32_e32 v48, v30, v30
	v_mul_f32_e32 v49, v31, v31
	v_mul_f32_e32 v42, 0x45800000, v52
	v_cndmask_b32_e32 v42, v52, v42, vcc
	v_mul_f32_e32 v42, v80, v42
	v_mul_f32_e32 v44, v70, v42
	v_mul_f32_e32 v45, v71, v42
	v_mul_f32_e32 v52, v18, v18
	v_mul_f32_e32 v53, v19, v19
	v_mul_f32_e32 v34, v34, v44
	v_mul_f32_e32 v35, v35, v45
	v_mul_f32_e32 v44, v72, v42
	v_mul_f32_e32 v45, v73, v42
	v_mov_b32_e32 v54, v52
	v_mul_f32_e32 v36, v36, v44
	v_mul_f32_e32 v37, v37, v45
	v_mul_f32_e32 v44, v66, v42
	v_mul_f32_e32 v45, v67, v42
	v_mul_f32_e32 v43, v69, v42
	v_mul_f32_e32 v42, v68, v42
	v_mul_f32_e32 v38, v38, v44
	v_mul_f32_e32 v39, v39, v45
	v_mul_f32_e32 v44, v26, v26
	v_mul_f32_e32 v45, v27, v27
	v_mul_f32_e32 v40, v40, v42
	v_mul_f32_e32 v41, v41, v43
	v_mul_f32_e32 v42, v28, v28
	v_mul_f32_e32 v43, v29, v29
	v_mov_b32_e32 v55, v44
	v_mov_b32_e32 v44, v53
	v_add_f32_e32 v44, v54, v44
	v_add_f32_e32 v45, v55, v45
	v_mov_b32_e32 v56, v50
	v_mov_b32_e32 v57, v42
	v_mul_f32_e32 v54, v22, v22
	v_mul_f32_e32 v55, v23, v23
	v_add_f32_e32 v44, v56, v44
	v_add_f32_e32 v45, v57, v45
	v_mov_b32_e32 v42, v51
	v_add_f32_e32 v42, v42, v44
	v_add_f32_e32 v43, v43, v45
	v_mov_b32_e32 v44, v54
	v_mov_b32_e32 v45, v48
	v_mul_f32_e32 v46, v32, v32
	v_mul_f32_e32 v47, v33, v33
	v_mul_f32_e32 v52, v24, v24
	v_mul_f32_e32 v53, v25, v25
	v_add_f32_e32 v42, v44, v42
	v_add_f32_e32 v43, v45, v43
	v_mov_b32_e32 v48, v55
	v_add_f32_e32 v42, v48, v42
	v_add_f32_e32 v43, v49, v43
	v_mov_b32_e32 v44, v52
	v_mov_b32_e32 v45, v46
	v_add_f32_e32 v42, v44, v42
	v_add_f32_e32 v43, v45, v43
	v_mov_b32_e32 v46, v53
	v_add_f32_e32 v42, v46, v42
	v_add_f32_e32 v43, v47, v43
	v_cvt_pk_bf16_f32 v34, v34, v35
	v_cvt_pk_bf16_f32 v35, v36, v37
	v_cvt_pk_bf16_f32 v36, v38, v39
	v_add_u32_e32 v46, 48, v116
	s_waitcnt lgkmcnt(0)
	v_add_f32_dpp v38, v42, v42 quad_perm:[1,0,3,2] row_mask:0xf bank_mask:0xf
	v_add_f32_dpp v39, v43, v43 quad_perm:[1,0,3,2] row_mask:0xf bank_mask:0xf
	v_ashrrev_i32_e32 v47, 31, v46
	v_cvt_pk_bf16_f32 v37, v40, v41
	v_lshl_add_u64 v[40:41], v[74:75], 0, v[46:47]
	v_lshlrev_b64 v[40:41], 7, v[40:41]
	s_waitcnt lgkmcnt(0)
	v_add_f32_dpp v38, v38, v38 quad_perm:[2,3,0,1] row_mask:0xf bank_mask:0xf
	v_add_f32_dpp v39, v39, v39 quad_perm:[2,3,0,1] row_mask:0xf bank_mask:0xf
	v_lshl_add_u64 v[40:41], v[76:77], 0, v[40:41]
	global_store_dwordx4 v[40:41], v[34:37], off
	v_readlane_b32 s24, v253, 24
	v_readlane_b32 s25, v253, 25
	s_waitcnt lgkmcnt(0)
	v_add_f32_dpp v36, v38, v38 row_half_mirror row_mask:0xf bank_mask:0xf
	v_add_f32_dpp v37, v39, v39 row_half_mirror row_mask:0xf bank_mask:0xf
	v_add_u32_e32 v34, 64, v116
	v_pk_fma_f32 v[36:37], v[36:37], s[6:7], v[78:79] op_sel_hi:[1,0,0]
	v_ashrrev_i32_e32 v35, 31, v34
	v_mul_f32_e32 v38, 0x4b800000, v37
	v_cmp_gt_f32_e32 vcc, s33, v37
	v_lshl_add_u64 v[34:35], v[74:75], 0, v[34:35]
	v_lshlrev_b64 v[34:35], 7, v[34:35]
	v_cndmask_b32_e32 v37, v37, v38, vcc
	v_rsq_f32_e32 v37, v37
	v_lshl_add_u64 v[34:35], v[76:77], 0, v[34:35]
	v_readlane_b32 s26, v253, 26
	v_readlane_b32 s27, v253, 27
	v_mul_f32_e32 v38, 0x45800000, v37
	v_cndmask_b32_e32 v37, v37, v38, vcc
	v_mul_f32_e32 v38, v80, v37
	v_mul_f32_e32 v40, v70, v38
	v_mul_f32_e32 v41, v71, v38
	v_cmp_gt_f32_e32 vcc, s33, v36
	v_mul_f32_e32 v26, v26, v40
	v_mul_f32_e32 v27, v27, v41
	v_mul_f32_e32 v40, v72, v38
	v_mul_f32_e32 v41, v73, v38
	v_cvt_pk_bf16_f32 v26, v26, v27
	v_mul_f32_e32 v28, v28, v40
	v_mul_f32_e32 v29, v29, v41
	v_mul_f32_e32 v40, v66, v38
	v_mul_f32_e32 v41, v67, v38
	v_cvt_pk_bf16_f32 v27, v28, v29
	v_mul_f32_e32 v28, 0x4b800000, v36
	v_cndmask_b32_e32 v28, v36, v28, vcc
	v_rsq_f32_e32 v36, v28
	v_mul_f32_e32 v39, v69, v38
	v_mul_f32_e32 v38, v68, v38
	v_mul_f32_e32 v30, v30, v40
	v_mul_f32_e32 v31, v31, v41
	v_mul_f32_e32 v32, v32, v38
	v_mul_f32_e32 v33, v33, v39
	v_cvt_pk_bf16_f32 v28, v30, v31
	v_cvt_pk_bf16_f32 v29, v32, v33
	global_store_dwordx4 v[34:35], v[26:29], off
	v_mul_f32_e32 v34, v4, v4
	v_mul_f32_e32 v35, v5, v5
	v_mul_f32_e32 v32, v14, v14
	v_mul_f32_e32 v33, v15, v15
	v_mul_f32_e32 v26, 0x45800000, v36
	v_cndmask_b32_e32 v26, v36, v26, vcc
	v_mul_f32_e32 v26, v80, v26
	v_mul_f32_e32 v28, v70, v26
	v_mul_f32_e32 v29, v71, v26
	v_mul_f32_e32 v36, v2, v2
	v_mul_f32_e32 v37, v3, v3
	v_mul_f32_e32 v18, v18, v28
	v_mul_f32_e32 v19, v19, v29
	v_mul_f32_e32 v28, v72, v26
	v_mul_f32_e32 v29, v73, v26
	v_mov_b32_e32 v38, v36
	v_mul_f32_e32 v20, v20, v28
	v_mul_f32_e32 v21, v21, v29
	v_mul_f32_e32 v28, v66, v26
	v_mul_f32_e32 v29, v67, v26
	v_mul_f32_e32 v27, v69, v26
	v_mul_f32_e32 v26, v68, v26
	v_mul_f32_e32 v22, v22, v28
	v_mul_f32_e32 v23, v23, v29
	v_mul_f32_e32 v28, v10, v10
	v_mul_f32_e32 v29, v11, v11
	v_mul_f32_e32 v24, v24, v26
	v_mul_f32_e32 v25, v25, v27
	v_mul_f32_e32 v26, v12, v12
	v_mul_f32_e32 v27, v13, v13
	v_mov_b32_e32 v39, v28
	v_mov_b32_e32 v28, v37
	v_add_f32_e32 v28, v38, v28
	v_add_f32_e32 v29, v39, v29
	v_mov_b32_e32 v40, v34
	v_mov_b32_e32 v41, v26
	v_mul_f32_e32 v38, v6, v6
	v_mul_f32_e32 v39, v7, v7
	v_add_f32_e32 v28, v40, v28
	v_add_f32_e32 v29, v41, v29
	v_mov_b32_e32 v26, v35
	v_add_f32_e32 v26, v26, v28
	v_add_f32_e32 v27, v27, v29
	v_mov_b32_e32 v28, v38
	v_mov_b32_e32 v29, v32
	v_mul_f32_e32 v30, v16, v16
	v_mul_f32_e32 v31, v17, v17
	v_mul_f32_e32 v36, v8, v8
	v_mul_f32_e32 v37, v9, v9
	v_add_f32_e32 v26, v28, v26
	v_add_f32_e32 v27, v29, v27
	v_mov_b32_e32 v32, v39
	v_add_f32_e32 v26, v32, v26
	v_add_f32_e32 v27, v33, v27
	v_mov_b32_e32 v28, v36
	v_mov_b32_e32 v29, v30
	v_add_f32_e32 v26, v28, v26
	v_add_f32_e32 v27, v29, v27
	v_mov_b32_e32 v30, v37
	v_add_f32_e32 v26, v30, v26
	v_add_f32_e32 v27, v31, v27
	v_cvt_pk_bf16_f32 v18, v18, v19
	v_cvt_pk_bf16_f32 v19, v20, v21
	v_cvt_pk_bf16_f32 v20, v22, v23
	v_add_u32_e32 v30, 0x50, v116
	s_waitcnt lgkmcnt(0)
	v_add_f32_dpp v22, v26, v26 quad_perm:[1,0,3,2] row_mask:0xf bank_mask:0xf
	v_add_f32_dpp v23, v27, v27 quad_perm:[1,0,3,2] row_mask:0xf bank_mask:0xf
	v_ashrrev_i32_e32 v31, 31, v30
	v_cvt_pk_bf16_f32 v21, v24, v25
	v_lshl_add_u64 v[24:25], v[74:75], 0, v[30:31]
	v_lshlrev_b64 v[24:25], 7, v[24:25]
	s_waitcnt lgkmcnt(0)
	v_add_f32_dpp v22, v22, v22 quad_perm:[2,3,0,1] row_mask:0xf bank_mask:0xf
	v_add_f32_dpp v23, v23, v23 quad_perm:[2,3,0,1] row_mask:0xf bank_mask:0xf
	v_lshl_add_u64 v[24:25], v[76:77], 0, v[24:25]
	global_store_dwordx4 v[24:25], v[18:21], off
	s_waitcnt lgkmcnt(0)
	s_nop 0
	v_add_f32_dpp v20, v22, v22 row_half_mirror row_mask:0xf bank_mask:0xf
	v_add_f32_dpp v21, v23, v23 row_half_mirror row_mask:0xf bank_mask:0xf
	v_add_u32_e32 v18, 0x60, v116
	v_pk_fma_f32 v[20:21], v[20:21], s[6:7], v[78:79] op_sel_hi:[1,0,0]
	v_ashrrev_i32_e32 v19, 31, v18
	v_mul_f32_e32 v22, 0x4b800000, v21
	v_cmp_gt_f32_e32 vcc, s33, v21
	v_lshl_add_u64 v[18:19], v[74:75], 0, v[18:19]
	v_lshlrev_b64 v[18:19], 7, v[18:19]
	v_cndmask_b32_e32 v21, v21, v22, vcc
	v_rsq_f32_e32 v21, v21
	v_lshl_add_u64 v[18:19], v[76:77], 0, v[18:19]
	v_mul_f32_e32 v22, 0x45800000, v21
	v_cndmask_b32_e32 v21, v21, v22, vcc
	v_mul_f32_e32 v22, v80, v21
	v_mul_f32_e32 v24, v70, v22
	v_mul_f32_e32 v25, v71, v22
	v_cmp_gt_f32_e32 vcc, s33, v20
	v_mul_f32_e32 v10, v10, v24
	v_mul_f32_e32 v11, v11, v25
	v_mul_f32_e32 v24, v72, v22
	v_mul_f32_e32 v25, v73, v22
	v_cvt_pk_bf16_f32 v10, v10, v11
	v_mul_f32_e32 v12, v12, v24
	v_mul_f32_e32 v13, v13, v25
	v_mul_f32_e32 v24, v66, v22
	v_mul_f32_e32 v25, v67, v22
	v_cvt_pk_bf16_f32 v11, v12, v13
	v_mul_f32_e32 v12, 0x4b800000, v20
	v_cndmask_b32_e32 v12, v20, v12, vcc
	v_rsq_f32_e32 v20, v12
	v_mul_f32_e32 v23, v69, v22
	v_mul_f32_e32 v22, v68, v22
	v_mul_f32_e32 v14, v14, v24
	v_mul_f32_e32 v15, v15, v25
	v_mul_f32_e32 v16, v16, v22
	v_mul_f32_e32 v17, v17, v23
	v_cvt_pk_bf16_f32 v12, v14, v15
	v_cvt_pk_bf16_f32 v13, v16, v17
	global_store_dwordx4 v[18:19], v[10:13], off
	s_nop 1
	v_mul_f32_e32 v10, 0x45800000, v20
	v_cndmask_b32_e32 v10, v20, v10, vcc
	v_mul_f32_e32 v10, v80, v10
	v_mul_f32_e32 v12, v70, v10
	v_mul_f32_e32 v13, v71, v10
	s_nop 0
	v_mul_f32_e32 v2, v2, v12
	v_mul_f32_e32 v3, v3, v13
	v_mul_f32_e32 v12, v72, v10
	v_mul_f32_e32 v13, v73, v10
	v_cvt_pk_bf16_f32 v2, v2, v3
	v_mul_f32_e32 v4, v4, v12
	v_mul_f32_e32 v5, v5, v13
	v_mul_f32_e32 v12, v66, v10
	v_mul_f32_e32 v13, v67, v10
	v_mul_f32_e32 v11, v69, v10
	v_mul_f32_e32 v10, v68, v10
	v_mul_f32_e32 v6, v6, v12
	v_mul_f32_e32 v7, v7, v13
	v_mul_f32_e32 v8, v8, v10
	v_mul_f32_e32 v9, v9, v11
	v_add_u32_e32 v10, 0x70, v116
	v_ashrrev_i32_e32 v11, 31, v10
	v_cvt_pk_bf16_f32 v3, v4, v5
	v_cvt_pk_bf16_f32 v4, v6, v7
	v_lshl_add_u64 v[6:7], v[74:75], 0, v[10:11]
	v_lshlrev_b64 v[6:7], 7, v[6:7]
	v_cvt_pk_bf16_f32 v5, v8, v9
	v_lshl_add_u64 v[6:7], v[76:77], 0, v[6:7]
	global_store_dwordx4 v[6:7], v[2:5], off
	s_branch .LBB0_240
